# up GEMM: next tile's first B1/A fragment LDS reads issued at the start of the current tile's epilogue (hidden behind the epilogue VALU)
# speedup vs baseline: 1.0041x; 1.0041x over previous
; #define PG8_STAGE(bufoff, gbase, voff) do { _Pragma("unroll") for (int _i = 0; _i < 2; ++_i) \
;         __builtin_amdgcn_global_load_lds((const unsigned*)((const char*)(gbase) + (voff)[_i]), (PG8_LAS unsigned*)(lds + (bufoff) + ldsw + _i * 8192), 16, 0, 0); } while (0)
; #define PG8_LDA(dst, b, h) do { _Pragma("unroll") for (int m = 0; m < 4; ++m) _Pragma("unroll") for (int k = 0; k < 2; ++k) dst[m][k] = *(const PG8_LAS bf16x8*)(lds + PG8_SA(b, h) + aoff + m * 2048 + k * 1024); } while (0)
; #define PG8_LDB(dst, b, h) do { _Pragma("unroll") for (int n = 0; n < 2; ++n) _Pragma("unroll") for (int k = 0; k < 2; ++k) dst[n][k] = *(const PG8_LAS bf16x8*)(lds + PG8_SB(b, h) + boff + n * 2048 + k * 1024); } while (0)
; #define PG8_WAIT_V(n) asm volatile("s_waitcnt vmcnt(" #n ")" ::: "memory")
; #define PG8_BAR __builtin_amdgcn_s_barrier()
; #define PG8_SCHED __builtin_amdgcn_sched_barrier(0)
; template <class Epi, class Sched, bool ALIGN_EPI = false, bool SP2 = false>
; __device__ __forceinline__ void gemm_phase(PG8_LAS unsigned char* lds, const Gemm g, const Sched& S, const Epi& E) {
;     ...
;         PG8_STAGE(PG8_SB(0, 0), cB, voffB); PG8_STAGE(PG8_SB(0, 1), cB + hstep, voffB); PG8_STAGE(PG8_SA(0, 0), cA, voffA); PG8_STAGE(PG8_SA(0, 1), cA + hstep, voffA);
;         if (wr == 1) PG8_BAR;
;         PG8_WAIT_V(2); PG8_BAR;
;         PG8_STAGE(PG8_SB(1, 0), cB + kstep, voffB); PG8_STAGE(PG8_SB(1, 1), cB + hstep + kstep, voffB);
;         PG8_WAIT_V(4); PG8_BAR;
;     ...
;             PG8_LDB(B0, 0, 0); PG8_LDB(B1, 0, 1); PG8_SCHED; PG8_LDA(At, 0, 0); PG8_STAGE(PG8_SA(1, 0), a1, voffA); PG8_STAGE(PG8_SA(1, 1), a1 + hstep, voffA);
.LBB0_595:
	s_add_u32 s72, s7, 0x25000000
	s_addc_u32 s73, s16, 0
	s_add_u32 s88, s7, 0x300000
	v_lshrrev_b32_e32 v12, 1, v10
	s_addc_u32 s89, s16, 0
	v_and_b32_e32 v12, 24, v12
	s_lshl_b32 s4, s4, 5
	v_and_b32_e32 v11, 15, v10
	v_lshlrev_b32_e32 v13, 1, v12
	v_lshlrev_b32_e32 v10, 2, v10
	s_and_b32 s7, s4, 0x60
	s_add_i32 m0, s37, 0x18000
	v_lshl_add_u64 v[0:1], v[0:1], 0, s[26:27]
	v_lshl_or_b32 v142, s5, 6, v11
	v_lshl_or_b32 v11, v11, 6, v13
	s_lshl_b32 s5, s5, 13
	v_and_b32_e32 v10, 32, v10
	s_lshl_b32 s4, s7, 7
	s_waitcnt vmcnt(2)
	s_barrier
	global_load_lds_dwordx4 v[0:1], off
	s_add_i32 m0, s37, 0x1a000
	v_bitop3_b32 v143, v11, s4, v10 bitop3:0xde
	s_add_u32 s4, s10, 0x80080
	v_bitop3_b32 v13, v11, s5, v10 bitop3:0xde
	v_lshl_add_u64 v[0:1], v[2:3], 0, s[26:27]
	s_addc_u32 s5, s11, 0
	global_load_lds_dwordx4 v[0:1], off
	s_add_i32 m0, s37, 0x1c000
	v_lshl_add_u64 v[0:1], s[4:5], 0, v[204:205]
	global_load_lds_dwordx4 v[0:1], off
	v_lshl_add_u64 v[0:1], s[4:5], 0, v[128:129]
	s_add_i32 m0, s37, 0x1e000
	s_cmpk_lt_u32 s6, 0x100
	global_load_lds_dwordx4 v[0:1], off
	v_lshlrev_b32_e32 v0, 15, v4
	v_and_b32_e32 v0, 0xffff0000, v0
	v_lshl_add_u32 v0, v5, 12, v0
	v_and_b32_e32 v1, 1, v4
	v_lshl_or_b32 v0, v1, 6, v0
	v_lshl_add_u32 v134, v6, 1, v0
	v_lshlrev_b32_e32 v0, 15, v8
	v_and_b32_e32 v0, 0xffff0000, v0
	s_waitcnt vmcnt(4)
	v_lshl_add_u32 v0, v7, 12, v0
	v_and_b32_e32 v1, 1, v8
	v_or_b32_e32 v144, s7, v12
	v_lshl_or_b32 v0, v1, 6, v0
	v_readlane_b32 s6, v255, 16
	v_mov_b32_e32 v133, v205
	v_mov_b32_e32 v131, v205
	s_cselect_b64 s[4:5], -1, 0
	v_mov_b32_e32 v135, v205
	v_lshl_add_u32 v136, v9, 1, v0
	v_mov_b32_e32 v137, v205
	s_mov_b32 s97, 0
	v_add_u32_e32 v145, 0, v13
	v_readlane_b32 s34, v255, 11
	s_mov_b32 s35, s6
	s_bitset1_b32 s35, 2
	s_lshl_b32 s34, s34, 1
	s_add_i32 s34, s34, s32
	s_barrier
	v_readlane_b32 s7, v255, 17
	v_add_u32_e32 v174, 0x14000, v143
	ds_read_b128 v[162:165], v174
	ds_read_b128 v[166:169], v174 offset:1024
	ds_read_b128 v[170:173], v174 offset:2048
	ds_read_b128 v[174:177], v174 offset:3072
	ds_read_b128 v[178:181], v145
	ds_read_b128 v[182:185], v145 offset:1024
	ds_read_b128 v[186:189], v145 offset:2048
	ds_read_b128 v[190:193], v145 offset:3072
	ds_read_b128 v[194:197], v145 offset:4096
	ds_read_b128 v[198:201], v145 offset:5120
	ds_read_b128 v[206:209], v145 offset:6144
	ds_read_b128 v[218:221], v145 offset:7168
	s_branch .LBB0_598

; #define PG8_STAGE(bufoff, gbase, voff) do { _Pragma("unroll") for (int _i = 0; _i < 2; ++_i) \
;         __builtin_amdgcn_global_load_lds((const unsigned*)((const char*)(gbase) + (voff)[_i]), (PG8_LAS unsigned*)(lds + (bufoff) + ldsw + _i * 8192), 16, 0, 0); } while (0)
; #define PG8_LDA(dst, b, h) do { _Pragma("unroll") for (int m = 0; m < 4; ++m) _Pragma("unroll") for (int k = 0; k < 2; ++k) dst[m][k] = *(const PG8_LAS bf16x8*)(lds + PG8_SA(b, h) + aoff + m * 2048 + k * 1024); } while (0)
; #define PG8_LDB(dst, b, h) do { _Pragma("unroll") for (int n = 0; n < 2; ++n) _Pragma("unroll") for (int k = 0; k < 2; ++k) dst[n][k] = *(const PG8_LAS bf16x8*)(lds + PG8_SB(b, h) + boff + n * 2048 + k * 1024); } while (0)
; #define PG8_MMA(ai, bj, At, Bt) do { __builtin_amdgcn_s_setprio(1); _Pragma("unroll") for (int m = 0; m < 4; ++m) _Pragma("unroll") for (int n = 0; n < 2; ++n) _Pragma("unroll") for (int k = 0; k < 2; ++k) \
;         acc[ai][bj][m][n] = __builtin_amdgcn_mfma_f32_16x16x32_bf16(Bt[n][k], At[m][k], acc[ai][bj][m][n], 0, 0, 0); __builtin_amdgcn_s_setprio(0); } while (0)
; #define PG8_WAIT_V(n) asm volatile("s_waitcnt vmcnt(" #n ")" ::: "memory")
; #define PG8_WAIT_L(n) asm volatile("s_waitcnt lgkmcnt(" #n ")" ::: "memory")
; template <class Epi, class Sched, bool ALIGN_EPI = false, bool SP2 = false>
; __device__ __forceinline__ void gemm_phase(PG8_LAS unsigned char* lds, const Gemm g, const Sched& S, const Epi& E) {
;     ...
;         const bool has_next = S.next(ui + 1, nxt);
;         const char* nA = has_next ? (const char*)g.A + (size_t)nxt.pm * tstep : cA; const char* nB = has_next ? (const char*)g.Bt + (size_t)nxt.pn * tstep : cB;
;         for (int t = 0; t < nt; t += 2) {
;             const bool last = (t == nt - 2);
;             const char* a1 = cA + (size_t)(t + 1) * kstep;
;             const char* a2 = last ? nA : cA + (size_t)(t + 2) * kstep; const char* b2 = last ? nB : cB + (size_t)(t + 2) * kstep;
;             const char* a3 = a2 + kstep; const char* b3 = b2 + kstep;
;             if (last && has_next) S.a_ready(nxt);
;             if constexpr (SP2) {
;             PG8_LDB(B0, 0, 0); PG8_LDB(B1, 0, 1); PG8_SCHED; PG8_LDA(At, 0, 0); PG8_STAGE(PG8_SA(1, 0), a1, voffA); PG8_STAGE(PG8_SA(1, 1), a1 + hstep, voffA);
;             PG8_WAIT_V(8); PG8_WAIT_L(0); PG8_BAR; PG8_MMA(0, 0, At, B0); PG8_MMA(0, 1, At, B1); PG8_BAR; PG8_SCHED;
.LBB0_604:
	s_ashr_i32 s95, s94, 31
	s_lshl_b64 s[16:17], s[94:95], 20
	s_add_u32 s16, s20, s16
	s_addc_u32 s17, s21, s17
	s_and_b64 s[44:45], s[42:43], exec
	s_cselect_b32 s95, s17, s9
	s_cselect_b32 s70, s16, s8
	s_ashr_i32 s7, s6, 31
	s_lshl_b64 s[44:45], s[6:7], 20
	s_add_u32 s44, s22, s44
	s_addc_u32 s45, s23, s45
	s_and_b64 s[52:53], s[42:43], exec
	s_cselect_b32 s7, s45, s11
	s_cselect_b32 s71, s44, s10
	s_add_u32 s79, s10, 0x100
	v_lshl_add_u64 v[138:139], s[8:9], 0, v[134:135]
	v_lshl_add_u64 v[140:141], s[8:9], 0, v[136:137]
	s_addc_u32 s52, s11, 0
	s_mov_b32 s53, -2
	s_mov_b64 vcc, 0
	v_lshl_add_u32 v240, s35, 8, v142
	v_ashrrev_i32_e32 v241, 31, v240
	v_lshl_add_u64 v[240:241], v[240:241], 2, s[88:89]
	global_load_dword v242, v[240:241], off
	global_load_dword v243, v[240:241], off offset:64
	global_load_dword v244, v[240:241], off offset:128
	global_load_dword v245, v[240:241], off offset:192
	global_load_dword v246, v[240:241], off offset:512
	global_load_dword v247, v[240:241], off offset:576
	global_load_dword v248, v[240:241], off offset:640
	global_load_dword v249, v[240:241], off offset:704
	s_add_u32 s10, s8, vcc_lo
	s_addc_u32 s11, s9, vcc_hi
	s_add_u32 s38, s10, 0x100
	s_addc_u32 s39, s11, 0
	s_add_u32 s10, s79, vcc_lo
	s_addc_u32 s11, s52, vcc_hi
	s_add_i32 s78, 0, 0x10000
	s_cmpk_eq_i32 vcc_lo, 0xf00
	s_cselect_b32 s11, s7, s11
	s_cselect_b32 s10, s71, s10
	s_cselect_b32 s69, s95, s39
	s_cselect_b32 s68, s70, s38
	s_add_i32 s92, 0, 0x14000
	v_add_u32_e32 v158, s78, v143
	ds_read_b128 v[146:149], v158
	ds_read_b128 v[150:153], v158 offset:1024
	ds_read_b128 v[154:157], v158 offset:2048
	ds_read_b128 v[158:161], v158 offset:3072
	v_lshl_add_u64 v[202:203], v[140:141], 0, vcc
	v_lshl_add_u64 v[222:223], v[202:203], 0, s[26:27]
	s_add_i32 m0, s37, 0x8000
	global_load_lds_dwordx4 v[222:223], off
	v_lshl_add_u64 v[222:223], v[138:139], 0, vcc
	v_lshl_add_u64 v[232:233], v[222:223], 0, s[26:27]
	s_add_i32 m0, s37, 0xa000
	v_lshl_add_u64 v[202:203], v[202:203], 0, s[28:29]
	global_load_lds_dwordx4 v[232:233], off
	s_add_i32 m0, s37, 0xc000
	s_nop 0
	global_load_lds_dwordx4 v[202:203], off
	v_lshl_add_u64 v[202:203], v[222:223], 0, s[28:29]
	s_add_i32 m0, s37, 0xe000
	s_nop 0
	global_load_lds_dwordx4 v[202:203], off
	s_waitcnt vmcnt(8)
	s_waitcnt lgkmcnt(0)
	s_barrier
	v_mfma_f32_16x16x32_bf16 v[124:127], v[146:149], v[178:181], 0
	v_mfma_f32_16x16x32_bf16 v[120:123], v[154:157], v[178:181], 0
	v_mfma_f32_16x16x32_bf16 v[108:111], v[146:149], v[186:189], 0
	v_mfma_f32_16x16x32_bf16 v[104:107], v[154:157], v[186:189], 0
	v_mfma_f32_16x16x32_bf16 v[92:95], v[146:149], v[194:197], 0
	v_mfma_f32_16x16x32_bf16 v[88:91], v[154:157], v[194:197], 0
	v_mfma_f32_16x16x32_bf16 v[76:79], v[146:149], v[206:209], 0
	v_mfma_f32_16x16x32_bf16 v[72:75], v[154:157], v[206:209], 0
	v_mfma_f32_16x16x32_bf16 v[124:127], v[150:153], v[182:185], v[124:127]
	v_mfma_f32_16x16x32_bf16 v[120:123], v[158:161], v[182:185], v[120:123]
	v_mfma_f32_16x16x32_bf16 v[108:111], v[150:153], v[190:193], v[108:111]
	v_mfma_f32_16x16x32_bf16 v[104:107], v[158:161], v[190:193], v[104:107]
	v_mfma_f32_16x16x32_bf16 v[92:95], v[150:153], v[198:201], v[92:95]
	v_mfma_f32_16x16x32_bf16 v[88:91], v[158:161], v[198:201], v[88:91]
	v_mfma_f32_16x16x32_bf16 v[76:79], v[150:153], v[218:221], v[76:79]
	v_mfma_f32_16x16x32_bf16 v[72:75], v[158:161], v[218:221], v[72:75]
	v_mfma_f32_16x16x32_bf16 v[116:119], v[162:165], v[178:181], 0
	v_mfma_f32_16x16x32_bf16 v[112:115], v[170:173], v[178:181], 0
	v_mfma_f32_16x16x32_bf16 v[100:103], v[162:165], v[186:189], 0
	v_mfma_f32_16x16x32_bf16 v[96:99], v[170:173], v[186:189], 0
	v_mfma_f32_16x16x32_bf16 v[84:87], v[162:165], v[194:197], 0
	v_mfma_f32_16x16x32_bf16 v[80:83], v[170:173], v[194:197], 0
	v_mfma_f32_16x16x32_bf16 v[68:71], v[162:165], v[206:209], 0
	v_mfma_f32_16x16x32_bf16 v[64:67], v[170:173], v[206:209], 0
	v_mfma_f32_16x16x32_bf16 v[116:119], v[166:169], v[182:185], v[116:119]
	v_mfma_f32_16x16x32_bf16 v[112:115], v[174:177], v[182:185], v[112:115]
	v_mfma_f32_16x16x32_bf16 v[100:103], v[166:169], v[190:193], v[100:103]
	v_mfma_f32_16x16x32_bf16 v[96:99], v[174:177], v[190:193], v[96:99]
	v_mfma_f32_16x16x32_bf16 v[84:87], v[166:169], v[198:201], v[84:87]
	v_mfma_f32_16x16x32_bf16 v[80:83], v[174:177], v[198:201], v[80:83]
	v_mfma_f32_16x16x32_bf16 v[68:71], v[166:169], v[218:221], v[68:71]
	v_mfma_f32_16x16x32_bf16 v[64:67], v[174:177], v[218:221], v[64:67]
	s_barrier
; #define PG8_STAGE(bufoff, gbase, voff) do { _Pragma("unroll") for (int _i = 0; _i < 2; ++_i) \
;         __builtin_amdgcn_global_load_lds((const unsigned*)((const char*)(gbase) + (voff)[_i]), (PG8_LAS unsigned*)(lds + (bufoff) + ldsw + _i * 8192), 16, 0, 0); } while (0)
; #define PG8_LDA(dst, b, h) do { _Pragma("unroll") for (int m = 0; m < 4; ++m) _Pragma("unroll") for (int k = 0; k < 2; ++k) dst[m][k] = *(const PG8_LAS bf16x8*)(lds + PG8_SA(b, h) + aoff + m * 2048 + k * 1024); } while (0)
; #define PG8_MMA(ai, bj, At, Bt) do { __builtin_amdgcn_s_setprio(1); _Pragma("unroll") for (int m = 0; m < 4; ++m) _Pragma("unroll") for (int n = 0; n < 2; ++n) _Pragma("unroll") for (int k = 0; k < 2; ++k) \
;         acc[ai][bj][m][n] = __builtin_amdgcn_mfma_f32_16x16x32_bf16(Bt[n][k], At[m][k], acc[ai][bj][m][n], 0, 0, 0); __builtin_amdgcn_s_setprio(0); } while (0)
; #define PG8_WAIT_V(n) asm volatile("s_waitcnt vmcnt(" #n ")" ::: "memory")
; #define PG8_WAIT_L(n) asm volatile("s_waitcnt lgkmcnt(" #n ")" ::: "memory")
; #define PG8_BAR __builtin_amdgcn_s_barrier()
; #define PG8_SCHED __builtin_amdgcn_sched_barrier(0)
; template <class Epi, class Sched, bool ALIGN_EPI = false, bool SP2 = false>
; __device__ __forceinline__ void gemm_phase(PG8_LAS unsigned char* lds, const Gemm g, const Sched& S, const Epi& E) {
;     ...
;             PG8_LDA(At, 0, 1); PG8_STAGE(PG8_SB(0, 0), b2, voffB); PG8_STAGE(PG8_SB(0, 1), b2 + hstep, voffB);
;             PG8_WAIT_V(6); PG8_WAIT_L(0); PG8_BAR; PG8_MMA(1, 0, At, B0); PG8_MMA(1, 1, At, B1); PG8_BAR; PG8_SCHED;
	s_add_i32 s38, s78, s36
	v_lshl_add_u64 v[202:203], s[10:11], 0, v[204:205]
	s_mov_b32 m0, s38
	ds_read_b128 v[178:181], v145 offset:16384
	ds_read_b128 v[182:185], v145 offset:17408
	ds_read_b128 v[186:189], v145 offset:18432
	ds_read_b128 v[190:193], v145 offset:19456
	ds_read_b128 v[194:197], v145 offset:20480
	ds_read_b128 v[198:201], v145 offset:21504
	ds_read_b128 v[206:209], v145 offset:22528
	ds_read_b128 v[218:221], v145 offset:23552
	global_load_lds_dwordx4 v[202:203], off
	s_add_i32 m0, s38, 0x2000
	s_add_u32 s38, s10, 0x80000
	v_lshl_add_u64 v[222:223], s[10:11], 0, v[128:129]
	s_addc_u32 s39, s11, 0
	s_add_i32 s78, s92, s36
	global_load_lds_dwordx4 v[222:223], off
	v_lshl_add_u64 v[232:233], s[38:39], 0, v[204:205]
	s_mov_b32 m0, s78
	s_nop 0
	global_load_lds_dwordx4 v[232:233], off
	v_lshl_add_u64 v[232:233], s[38:39], 0, v[128:129]
	s_add_i32 m0, s78, 0x2000
	s_nop 0
	global_load_lds_dwordx4 v[232:233], off
	s_waitcnt vmcnt(6)
	s_waitcnt lgkmcnt(0)
	s_barrier
	v_mfma_f32_16x16x32_bf16 v[60:63], v[146:149], v[178:181], 0
	v_mfma_f32_16x16x32_bf16 v[56:59], v[154:157], v[178:181], 0
	v_mfma_f32_16x16x32_bf16 v[44:47], v[146:149], v[186:189], 0
	v_mfma_f32_16x16x32_bf16 v[40:43], v[154:157], v[186:189], 0
	v_mfma_f32_16x16x32_bf16 v[28:31], v[146:149], v[194:197], 0
	v_mfma_f32_16x16x32_bf16 v[24:27], v[154:157], v[194:197], 0
	v_mfma_f32_16x16x32_bf16 v[12:15], v[146:149], v[206:209], 0
	v_mfma_f32_16x16x32_bf16 v[8:11], v[154:157], v[206:209], 0
	v_mfma_f32_16x16x32_bf16 v[60:63], v[150:153], v[182:185], v[60:63]
	v_mfma_f32_16x16x32_bf16 v[56:59], v[158:161], v[182:185], v[56:59]
	v_mfma_f32_16x16x32_bf16 v[44:47], v[150:153], v[190:193], v[44:47]
	v_mfma_f32_16x16x32_bf16 v[40:43], v[158:161], v[190:193], v[40:43]
	v_mfma_f32_16x16x32_bf16 v[28:31], v[150:153], v[198:201], v[28:31]
	v_mfma_f32_16x16x32_bf16 v[24:27], v[158:161], v[198:201], v[24:27]
	v_mfma_f32_16x16x32_bf16 v[12:15], v[150:153], v[218:221], v[12:15]
	v_mfma_f32_16x16x32_bf16 v[8:11], v[158:161], v[218:221], v[8:11]
	v_mfma_f32_16x16x32_bf16 v[52:55], v[162:165], v[178:181], 0
	v_mfma_f32_16x16x32_bf16 v[48:51], v[170:173], v[178:181], 0
	v_mfma_f32_16x16x32_bf16 v[36:39], v[162:165], v[186:189], 0
	v_mfma_f32_16x16x32_bf16 v[32:35], v[170:173], v[186:189], 0
	v_mfma_f32_16x16x32_bf16 v[20:23], v[162:165], v[194:197], 0
	v_mfma_f32_16x16x32_bf16 v[16:19], v[170:173], v[194:197], 0
	v_mfma_f32_16x16x32_bf16 v[4:7], v[162:165], v[206:209], 0
	v_mfma_f32_16x16x32_bf16 v[0:3], v[170:173], v[206:209], 0
	v_mfma_f32_16x16x32_bf16 v[52:55], v[166:169], v[182:185], v[52:55]
	v_mfma_f32_16x16x32_bf16 v[48:51], v[174:177], v[182:185], v[48:51]
	v_mfma_f32_16x16x32_bf16 v[36:39], v[166:169], v[190:193], v[36:39]
	v_mfma_f32_16x16x32_bf16 v[32:35], v[174:177], v[190:193], v[32:35]
	v_mfma_f32_16x16x32_bf16 v[20:23], v[166:169], v[198:201], v[20:23]
	v_mfma_f32_16x16x32_bf16 v[16:19], v[174:177], v[198:201], v[16:19]
	v_mfma_f32_16x16x32_bf16 v[4:7], v[166:169], v[218:221], v[4:7]
	v_mfma_f32_16x16x32_bf16 v[0:3], v[174:177], v[218:221], v[0:3]
	s_barrier
	s_branch .Lpl_up

; __device__ __forceinline__ unsigned cvt_pk_bf16(float lo, float hi) { unsigned r; asm volatile("v_cvt_pk_bf16_f32 %0, %1, %2" : "=v"(r) : "v"(lo), "v"(hi)); return r; }
; #define PG8_STAGE(bufoff, gbase, voff) do { _Pragma("unroll") for (int _i = 0; _i < 2; ++_i) \
;         __builtin_amdgcn_global_load_lds((const unsigned*)((const char*)(gbase) + (voff)[_i]), (PG8_LAS unsigned*)(lds + (bufoff) + ldsw + _i * 8192), 16, 0, 0); } while (0)
;     __device__ __forceinline__ void operator()(const f32x4 (&acc)[2][2][4][2], const Unit& u, int wr, int wc, int fr, int fq) const {
;         const int row0 = u.pm * BM + wr * 64 + fr; const int colt = u.pn * BM;
;         const float sc = (colt < scale_cols) ? scale0 : 1.f;
;         const int col0 = colt + wc * 32 + 8 * fq;
;         f32x4 cs[2][2];
; #pragma unroll
;         for (int bj = 0; bj < 2; ++bj) { cs[bj][0] = (f32x4){1.f, 1.f, 1.f, 1.f}; cs[bj][1] = cs[bj][0]; if (rsmode == 2) { cs[bj][0] = *(const f32x4*)(rs + col0 + bj * HALF); cs[bj][1] = *(const f32x4*)(rs + col0 + bj * HALF + 4); } }
; #pragma unroll
;         for (int ai = 0; ai < 2; ++ai)
; #pragma unroll
;             for (int m = 0; m < 4; ++m) { bf16_t* rowp = O + (size_t)(row0 + ai * HALF + m * 16) * ldc + col0;
;                 float rsc = sc; if (rsmode == 1) { const float r_ = rs[row0 + ai * HALF + m * 16]; rsc = sc * (ACT == 2 ? r_ * r_ : r_); }
; #pragma unroll
;                 for (int bj = 0; bj < 2; ++bj) { f32x4 v0 = acc[ai][bj][m][0], v1 = acc[ai][bj][m][1];
;                     if (ACT == 2) {
; #pragma unroll
;                         for (int e = 0; e < 4; ++e) { const float a0 = fmaxf(v0[e], 0.f), a1 = fmaxf(v1[e], 0.f); v0[e] = a0 * a0; v1[e] = a1 * a1; } }
;                     v0 = v0 * cs[bj][0] * rsc; v1 = v1 * cs[bj][1] * rsc; u32x4 w; w.x = cvt_pk_bf16(v0[0], v0[1]); w.y = cvt_pk_bf16(v0[2], v0[3]); w.z = cvt_pk_bf16(v1[0], v1[1]); w.w = cvt_pk_bf16(v1[2], v1[3]);
;                     *(u32x4*)(rowp + bj * HALF) = w; } }
; template <class Epi, class Sched, bool ALIGN_EPI = false, bool SP2 = false>
; __device__ __forceinline__ void gemm_phase(PG8_LAS unsigned char* lds, const Gemm g, const Sched& S, const Epi& E) {
;     ...
;             PG8_LDB(B0, 0, 0); PG8_LDB(B1, 0, 1); PG8_SCHED; PG8_LDA(At, 0, 0); PG8_STAGE(PG8_SA(1, 0), a1, voffA); PG8_STAGE(PG8_SA(1, 1), a1 + hstep, voffA);
.LBB0_608:
	v_add_u32_e32 v174, 0x14000, v143
	ds_read_b128 v[162:165], v174
	ds_read_b128 v[166:169], v174 offset:1024
	ds_read_b128 v[170:173], v174 offset:2048
	ds_read_b128 v[174:177], v174 offset:3072
	ds_read_b128 v[178:181], v145
	ds_read_b128 v[182:185], v145 offset:1024
	ds_read_b128 v[186:189], v145 offset:2048
	ds_read_b128 v[190:193], v145 offset:3072
	ds_read_b128 v[194:197], v145 offset:4096
	ds_read_b128 v[198:201], v145 offset:5120
	ds_read_b128 v[206:209], v145 offset:6144
	ds_read_b128 v[218:221], v145 offset:7168
	v_lshl_add_u32 v140, s35, 8, v142
	v_ashrrev_i32_e32 v141, 31, v140
	v_lshl_add_u64 v[138:139], v[140:141], 2, s[88:89]
	s_nop 0
	v_lshl_or_b32 v146, s34, 8, v144
	v_max_f32_e32 v152, v118, v118
	v_max_f32_e32 v153, v119, v119
	v_max_f32_e32 v118, 0, v126
	v_max_f32_e32 v119, 0, v127
	v_max_f32_e32 v148, v116, v116
	v_max_f32_e32 v149, v112, v112
	v_max_f32_e32 v150, v117, v117
	v_max_f32_e32 v151, v113, v113
	v_ashrrev_i32_e32 v147, 31, v146
	v_max_f32_e32 v112, 0, v124
	v_max_f32_e32 v116, 0, v120
	v_max_f32_e32 v113, 0, v125
	v_max_f32_e32 v117, 0, v121
	v_max_f32_e32 v120, 0, v122
	v_max_f32_e32 v121, 0, v123
	v_max_f32_e32 v126, 0, v152
	v_max_f32_e32 v127, 0, v153
	v_lshlrev_b64 v[152:153], 14, v[140:141]
	v_pk_mul_f32 v[118:119], v[118:119], v[118:119]
	v_max_f32_e32 v122, 0, v148
	v_max_f32_e32 v124, 0, v149
	v_max_f32_e32 v123, 0, v150
	v_max_f32_e32 v125, 0, v151
	v_max_f32_e32 v148, 0, v114
	v_max_f32_e32 v149, 0, v115
	v_or_b32_e32 v150, 16, v140
	v_lshlrev_b64 v[114:115], 1, v[146:147]
	v_pk_mul_f32 v[146:147], v[112:113], v[112:113]
	v_pk_mul_f32 v[116:117], v[116:117], v[116:117]
	v_pk_mul_f32 v[120:121], v[120:121], v[120:121]
	v_lshl_add_u64 v[112:113], s[72:73], 0, v[152:153]
	v_pk_mul_f32 v[122:123], v[122:123], v[122:123]
	v_pk_mul_f32 v[126:127], v[126:127], v[126:127]
	v_pk_mul_f32 v[124:125], v[124:125], v[124:125]
	v_pk_mul_f32 v[148:149], v[148:149], v[148:149]
	v_ashrrev_i32_e32 v151, 31, v150
	v_lshl_add_u64 v[112:113], v[112:113], 0, v[114:115]
	v_lshl_add_u64 v[152:153], v[150:151], 2, s[88:89]
	v_mul_f32_e32 v154, v242, v242
	v_pk_mul_f32 v[118:119], v[118:119], v[154:155] op_sel_hi:[1,0]
	v_pk_mul_f32 v[146:147], v[146:147], v[154:155] op_sel_hi:[1,0]
	v_pk_mul_f32 v[120:121], v[120:121], v[154:155] op_sel_hi:[1,0]
	v_pk_mul_f32 v[156:157], v[116:117], v[154:155] op_sel_hi:[1,0]
	v_cvt_pk_bf16_f32 v116, v146, v147
	v_cvt_pk_bf16_f32 v117, v118, v119
	v_pk_mul_f32 v[126:127], v[126:127], v[154:155] op_sel_hi:[1,0]
	v_cvt_pk_bf16_f32 v118, v156, v157
	v_cvt_pk_bf16_f32 v119, v120, v121
	v_pk_mul_f32 v[122:123], v[122:123], v[154:155] op_sel_hi:[1,0]
	v_pk_mul_f32 v[148:149], v[148:149], v[154:155] op_sel_hi:[1,0]
	v_pk_mul_f32 v[124:125], v[124:125], v[154:155] op_sel_hi:[1,0]
	global_store_dwordx4 v[112:113], v[116:119], off
	v_max_f32_e32 v121, v98, v98
	v_max_f32_e32 v98, 0, v104
	v_cvt_pk_bf16_f32 v116, v122, v123
	v_cvt_pk_bf16_f32 v117, v126, v127
	v_cvt_pk_bf16_f32 v118, v124, v125
	v_cvt_pk_bf16_f32 v119, v148, v149
	global_store_dwordx4 v[112:113], v[116:119], off offset:256
	s_nop 0
	v_max_f32_e32 v124, v99, v99
	v_max_f32_e32 v117, v96, v96
	v_max_f32_e32 v118, v101, v101
	v_max_f32_e32 v119, v97, v97
	v_max_f32_e32 v96, 0, v108
	v_max_f32_e32 v97, 0, v109
	v_max_f32_e32 v99, 0, v105
	v_max_f32_e32 v116, v100, v100
	v_max_f32_e32 v120, v102, v102
	v_max_f32_e32 v123, v103, v103
	v_max_f32_e32 v100, 0, v110
	v_max_f32_e32 v102, 0, v106
	v_max_f32_e32 v101, 0, v111
	v_max_f32_e32 v103, 0, v107
	v_max_f32_e32 v105, 0, v118
	v_max_f32_e32 v107, 0, v119
	v_pk_mul_f32 v[96:97], v[96:97], v[96:97]
	v_pk_mul_f32 v[98:99], v[98:99], v[98:99]
	v_lshlrev_b64 v[118:119], 14, v[150:151]
	v_max_f32_e32 v104, 0, v116
	v_max_f32_e32 v106, 0, v117
	v_max_f32_e32 v108, 0, v120
	v_max_f32_e32 v110, 0, v121
	v_max_f32_e32 v109, 0, v123
	v_max_f32_e32 v111, 0, v124
	v_or_b32_e32 v116, 32, v140
	v_pk_mul_f32 v[100:101], v[100:101], v[100:101]
	v_pk_mul_f32 v[102:103], v[102:103], v[102:103]
	v_lshl_add_u64 v[118:119], s[72:73], 0, v[118:119]
	v_pk_mul_f32 v[104:105], v[104:105], v[104:105]
	v_pk_mul_f32 v[108:109], v[108:109], v[108:109]
	v_pk_mul_f32 v[106:107], v[106:107], v[106:107]
	v_pk_mul_f32 v[110:111], v[110:111], v[110:111]
	v_ashrrev_i32_e32 v117, 31, v116
	v_lshl_add_u64 v[118:119], v[118:119], 0, v[114:115]
	v_lshl_add_u64 v[120:121], v[116:117], 2, s[88:89]
	s_mov_b32 s7, 0x200000
	s_mov_b64 s[8:9], 0x200000
	v_mul_f32_e32 v122, v243, v243
	v_pk_mul_f32 v[96:97], v[96:97], v[122:123] op_sel_hi:[1,0]
	v_pk_mul_f32 v[98:99], v[98:99], v[122:123] op_sel_hi:[1,0]
	v_pk_mul_f32 v[100:101], v[100:101], v[122:123] op_sel_hi:[1,0]
	v_pk_mul_f32 v[102:103], v[102:103], v[122:123] op_sel_hi:[1,0]
	v_cvt_pk_bf16_f32 v96, v96, v97
	v_cvt_pk_bf16_f32 v97, v100, v101
	v_cvt_pk_bf16_f32 v98, v98, v99
	v_pk_mul_f32 v[108:109], v[108:109], v[122:123] op_sel_hi:[1,0]
	v_cvt_pk_bf16_f32 v99, v102, v103
	v_pk_mul_f32 v[104:105], v[104:105], v[122:123] op_sel_hi:[1,0]
	v_pk_mul_f32 v[110:111], v[110:111], v[122:123] op_sel_hi:[1,0]
	v_pk_mul_f32 v[106:107], v[106:107], v[122:123] op_sel_hi:[1,0]
	global_store_dwordx4 v[118:119], v[96:99], off
	v_max_f32_e32 v101, v82, v82
	v_max_f32_e32 v82, 0, v88
	v_cvt_pk_bf16_f32 v96, v104, v105
	v_cvt_pk_bf16_f32 v97, v108, v109
	v_cvt_pk_bf16_f32 v98, v106, v107
	v_cvt_pk_bf16_f32 v99, v110, v111
	global_store_dwordx4 v[118:119], v[96:99], off offset:256
	s_nop 0
	v_max_f32_e32 v104, v83, v83
	v_max_f32_e32 v97, v80, v80
	v_max_f32_e32 v98, v85, v85
	v_max_f32_e32 v99, v81, v81
	v_max_f32_e32 v80, 0, v92
	v_max_f32_e32 v81, 0, v93
	v_max_f32_e32 v83, 0, v89
; __device__ __forceinline__ unsigned cvt_pk_bf16(float lo, float hi) { unsigned r; asm volatile("v_cvt_pk_bf16_f32 %0, %1, %2" : "=v"(r) : "v"(lo), "v"(hi)); return r; }
;     __device__ __forceinline__ void operator()(const f32x4 (&acc)[2][2][4][2], const Unit& u, int wr, int wc, int fr, int fq) const {
;     ...
;             for (int m = 0; m < 4; ++m) { bf16_t* rowp = O + (size_t)(row0 + ai * HALF + m * 16) * ldc + col0;
;                 float rsc = sc; if (rsmode == 1) { const float r_ = rs[row0 + ai * HALF + m * 16]; rsc = sc * (ACT == 2 ? r_ * r_ : r_); }
; #pragma unroll
;                 for (int bj = 0; bj < 2; ++bj) { f32x4 v0 = acc[ai][bj][m][0], v1 = acc[ai][bj][m][1];
;                     if (ACT == 2) {
; #pragma unroll
;                         for (int e = 0; e < 4; ++e) { const float a0 = fmaxf(v0[e], 0.f), a1 = fmaxf(v1[e], 0.f); v0[e] = a0 * a0; v1[e] = a1 * a1; } }
;                     v0 = v0 * cs[bj][0] * rsc; v1 = v1 * cs[bj][1] * rsc; u32x4 w; w.x = cvt_pk_bf16(v0[0], v0[1]); w.y = cvt_pk_bf16(v0[2], v0[3]); w.z = cvt_pk_bf16(v1[0], v1[1]); w.w = cvt_pk_bf16(v1[2], v1[3]);
;                     *(u32x4*)(rowp + bj * HALF) = w; } }
	v_max_f32_e32 v96, v84, v84
	v_max_f32_e32 v100, v86, v86
	v_max_f32_e32 v103, v87, v87
	v_max_f32_e32 v84, 0, v94
	v_max_f32_e32 v86, 0, v90
	v_max_f32_e32 v85, 0, v95
	v_max_f32_e32 v87, 0, v91
	v_max_f32_e32 v89, 0, v98
	v_max_f32_e32 v91, 0, v99
	v_pk_mul_f32 v[80:81], v[80:81], v[80:81]
	v_pk_mul_f32 v[82:83], v[82:83], v[82:83]
	v_lshlrev_b64 v[98:99], 14, v[116:117]
	v_max_f32_e32 v88, 0, v96
	v_max_f32_e32 v90, 0, v97
	v_max_f32_e32 v92, 0, v100
	v_max_f32_e32 v94, 0, v101
	v_max_f32_e32 v93, 0, v103
	v_max_f32_e32 v95, 0, v104
	v_or_b32_e32 v96, 48, v140
	v_pk_mul_f32 v[84:85], v[84:85], v[84:85]
	v_pk_mul_f32 v[86:87], v[86:87], v[86:87]
	v_lshl_add_u64 v[98:99], s[72:73], 0, v[98:99]
	v_pk_mul_f32 v[88:89], v[88:89], v[88:89]
	v_pk_mul_f32 v[92:93], v[92:93], v[92:93]
	v_pk_mul_f32 v[90:91], v[90:91], v[90:91]
	v_pk_mul_f32 v[94:95], v[94:95], v[94:95]
	v_ashrrev_i32_e32 v97, 31, v96
	v_lshl_add_u64 v[98:99], v[98:99], 0, v[114:115]
	v_lshl_add_u64 v[100:101], v[96:97], 2, s[88:89]
	v_mul_f32_e32 v102, v244, v244
	v_pk_mul_f32 v[80:81], v[80:81], v[102:103] op_sel_hi:[1,0]
	v_pk_mul_f32 v[82:83], v[82:83], v[102:103] op_sel_hi:[1,0]
	v_pk_mul_f32 v[84:85], v[84:85], v[102:103] op_sel_hi:[1,0]
	v_pk_mul_f32 v[86:87], v[86:87], v[102:103] op_sel_hi:[1,0]
	v_cvt_pk_bf16_f32 v80, v80, v81
	v_cvt_pk_bf16_f32 v81, v84, v85
	v_cvt_pk_bf16_f32 v82, v82, v83
	v_pk_mul_f32 v[92:93], v[92:93], v[102:103] op_sel_hi:[1,0]
	v_cvt_pk_bf16_f32 v83, v86, v87
	v_pk_mul_f32 v[88:89], v[88:89], v[102:103] op_sel_hi:[1,0]
	v_pk_mul_f32 v[94:95], v[94:95], v[102:103] op_sel_hi:[1,0]
	v_pk_mul_f32 v[90:91], v[90:91], v[102:103] op_sel_hi:[1,0]
	global_store_dwordx4 v[98:99], v[80:83], off
	v_max_f32_e32 v84, v65, v65
	v_max_f32_e32 v86, v66, v66
	v_cvt_pk_bf16_f32 v80, v88, v89
	v_cvt_pk_bf16_f32 v81, v92, v93
	v_cvt_pk_bf16_f32 v82, v90, v91
	v_cvt_pk_bf16_f32 v83, v94, v95
	global_store_dwordx4 v[98:99], v[80:83], off offset:256
	s_nop 0
	v_max_f32_e32 v88, v67, v67
	v_max_f32_e32 v80, v68, v68
	v_max_f32_e32 v81, v64, v64
	v_max_f32_e32 v64, 0, v76
	v_max_f32_e32 v66, 0, v72
	v_max_f32_e32 v65, 0, v77
	v_max_f32_e32 v67, 0, v73
	v_max_f32_e32 v83, v69, v69
	v_max_f32_e32 v85, v70, v70
	v_max_f32_e32 v87, v71, v71
	v_max_f32_e32 v68, 0, v78
	v_max_f32_e32 v70, 0, v74
	v_max_f32_e32 v69, 0, v79
	v_max_f32_e32 v71, 0, v75
	v_max_f32_e32 v72, 0, v80
	v_max_f32_e32 v74, 0, v81
	v_pk_mul_f32 v[64:65], v[64:65], v[64:65]
	v_pk_mul_f32 v[66:67], v[66:67], v[66:67]
	v_lshlrev_b64 v[80:81], 14, v[96:97]
	v_max_f32_e32 v73, 0, v83
	v_max_f32_e32 v75, 0, v84
	v_max_f32_e32 v76, 0, v85
	v_max_f32_e32 v78, 0, v86
	v_max_f32_e32 v77, 0, v87
	v_max_f32_e32 v79, 0, v88
	v_pk_mul_f32 v[68:69], v[68:69], v[68:69]
	v_pk_mul_f32 v[70:71], v[70:71], v[70:71]
	v_lshl_add_u64 v[80:81], s[72:73], 0, v[80:81]
	v_pk_mul_f32 v[72:73], v[72:73], v[72:73]
	v_pk_mul_f32 v[76:77], v[76:77], v[76:77]
	v_pk_mul_f32 v[74:75], v[74:75], v[74:75]
	v_pk_mul_f32 v[78:79], v[78:79], v[78:79]
	v_lshl_add_u64 v[80:81], v[80:81], 0, v[114:115]
	v_mul_f32_e32 v82, v245, v245
	v_pk_mul_f32 v[64:65], v[64:65], v[82:83] op_sel_hi:[1,0]
	v_pk_mul_f32 v[66:67], v[66:67], v[82:83] op_sel_hi:[1,0]
	v_pk_mul_f32 v[68:69], v[68:69], v[82:83] op_sel_hi:[1,0]
	v_pk_mul_f32 v[70:71], v[70:71], v[82:83] op_sel_hi:[1,0]
	v_cvt_pk_bf16_f32 v64, v64, v65
	v_cvt_pk_bf16_f32 v65, v68, v69
	v_cvt_pk_bf16_f32 v66, v66, v67
	v_pk_mul_f32 v[76:77], v[76:77], v[82:83] op_sel_hi:[1,0]
	v_cvt_pk_bf16_f32 v67, v70, v71
	v_pk_mul_f32 v[72:73], v[72:73], v[82:83] op_sel_hi:[1,0]
	v_pk_mul_f32 v[78:79], v[78:79], v[82:83] op_sel_hi:[1,0]
	v_pk_mul_f32 v[74:75], v[74:75], v[82:83] op_sel_hi:[1,0]
	global_store_dwordx4 v[80:81], v[64:67], off
	v_max_f32_e32 v70, v50, v50
	v_max_f32_e32 v50, 0, v56
	v_cvt_pk_bf16_f32 v64, v72, v73
	v_cvt_pk_bf16_f32 v65, v76, v77
	v_cvt_pk_bf16_f32 v66, v74, v75
	v_cvt_pk_bf16_f32 v67, v78, v79
	global_store_dwordx4 v[80:81], v[64:67], off offset:256
	s_nop 0
	v_max_f32_e32 v72, v51, v51
	v_max_f32_e32 v65, v48, v48
	v_max_f32_e32 v67, v49, v49
	v_max_f32_e32 v48, 0, v60
	v_max_f32_e32 v49, 0, v61
	v_max_f32_e32 v51, 0, v57
	v_max_f32_e32 v64, v52, v52
	v_max_f32_e32 v66, v53, v53
	v_max_f32_e32 v69, v54, v54
	v_max_f32_e32 v71, v55, v55
	v_max_f32_e32 v52, 0, v62
	v_max_f32_e32 v54, 0, v58
	v_max_f32_e32 v53, 0, v63
	v_max_f32_e32 v55, 0, v59
	v_pk_mul_f32 v[48:49], v[48:49], v[48:49]
	v_pk_mul_f32 v[50:51], v[50:51], v[50:51]
	v_max_f32_e32 v56, 0, v64
	v_max_f32_e32 v58, 0, v65
	v_max_f32_e32 v57, 0, v66
	v_max_f32_e32 v59, 0, v67
	v_max_f32_e32 v60, 0, v69
	v_max_f32_e32 v62, 0, v70
	v_max_f32_e32 v61, 0, v71
	v_max_f32_e32 v63, 0, v72
	v_pk_mul_f32 v[52:53], v[52:53], v[52:53]
	v_pk_mul_f32 v[54:55], v[54:55], v[54:55]
	v_add_co_u32_e32 v66, vcc, s7, v112
	v_pk_mul_f32 v[56:57], v[56:57], v[56:57]
	v_pk_mul_f32 v[60:61], v[60:61], v[60:61]
	v_pk_mul_f32 v[58:59], v[58:59], v[58:59]
	v_pk_mul_f32 v[62:63], v[62:63], v[62:63]
	v_lshl_add_u64 v[64:65], v[112:113], 0, s[8:9]
	v_addc_co_u32_e32 v67, vcc, 0, v113, vcc
	s_mov_b32 s7, 0x240000
	s_mov_b64 s[8:9], 0x240000
	v_mul_f32_e32 v68, v246, v246
	v_pk_mul_f32 v[48:49], v[48:49], v[68:69] op_sel_hi:[1,0]
	v_pk_mul_f32 v[50:51], v[50:51], v[68:69] op_sel_hi:[1,0]
	v_pk_mul_f32 v[52:53], v[52:53], v[68:69] op_sel_hi:[1,0]
	v_pk_mul_f32 v[54:55], v[54:55], v[68:69] op_sel_hi:[1,0]
	v_cvt_pk_bf16_f32 v48, v48, v49
	v_cvt_pk_bf16_f32 v49, v52, v53
	v_cvt_pk_bf16_f32 v50, v50, v51
	v_pk_mul_f32 v[60:61], v[60:61], v[68:69] op_sel_hi:[1,0]
	v_cvt_pk_bf16_f32 v51, v54, v55
	v_pk_mul_f32 v[56:57], v[56:57], v[68:69] op_sel_hi:[1,0]
; __device__ __forceinline__ unsigned cvt_pk_bf16(float lo, float hi) { unsigned r; asm volatile("v_cvt_pk_bf16_f32 %0, %1, %2" : "=v"(r) : "v"(lo), "v"(hi)); return r; }
;     __device__ __forceinline__ void operator()(const f32x4 (&acc)[2][2][4][2], const Unit& u, int wr, int wc, int fr, int fq) const {
;     ...
;             for (int m = 0; m < 4; ++m) { bf16_t* rowp = O + (size_t)(row0 + ai * HALF + m * 16) * ldc + col0;
;                 float rsc = sc; if (rsmode == 1) { const float r_ = rs[row0 + ai * HALF + m * 16]; rsc = sc * (ACT == 2 ? r_ * r_ : r_); }
; #pragma unroll
;                 for (int bj = 0; bj < 2; ++bj) { f32x4 v0 = acc[ai][bj][m][0], v1 = acc[ai][bj][m][1];
;                     if (ACT == 2) {
; #pragma unroll
;                         for (int e = 0; e < 4; ++e) { const float a0 = fmaxf(v0[e], 0.f), a1 = fmaxf(v1[e], 0.f); v0[e] = a0 * a0; v1[e] = a1 * a1; } }
;                     v0 = v0 * cs[bj][0] * rsc; v1 = v1 * cs[bj][1] * rsc; u32x4 w; w.x = cvt_pk_bf16(v0[0], v0[1]); w.y = cvt_pk_bf16(v0[2], v0[3]); w.z = cvt_pk_bf16(v1[0], v1[1]); w.w = cvt_pk_bf16(v1[2], v1[3]);
;                     *(u32x4*)(rowp + bj * HALF) = w; } }
	v_pk_mul_f32 v[62:63], v[62:63], v[68:69] op_sel_hi:[1,0]
	v_pk_mul_f32 v[58:59], v[58:59], v[68:69] op_sel_hi:[1,0]
	global_store_dwordx4 v[66:67], v[48:51], off
	v_max_f32_e32 v54, v34, v34
	v_max_f32_e32 v34, 0, v40
	v_cvt_pk_bf16_f32 v48, v56, v57
	v_cvt_pk_bf16_f32 v49, v60, v61
	v_cvt_pk_bf16_f32 v50, v58, v59
	v_cvt_pk_bf16_f32 v51, v62, v63
	global_store_dwordx4 v[64:65], v[48:51], off offset:256
	s_nop 0
	v_max_f32_e32 v56, v35, v35
	v_max_f32_e32 v49, v32, v32
	v_max_f32_e32 v51, v33, v33
	v_max_f32_e32 v32, 0, v44
	v_max_f32_e32 v33, 0, v45
	v_max_f32_e32 v35, 0, v41
	v_max_f32_e32 v48, v36, v36
	v_max_f32_e32 v50, v37, v37
	v_max_f32_e32 v53, v38, v38
	v_max_f32_e32 v55, v39, v39
	v_max_f32_e32 v36, 0, v46
	v_max_f32_e32 v38, 0, v42
	v_max_f32_e32 v37, 0, v47
	v_max_f32_e32 v39, 0, v43
	v_pk_mul_f32 v[32:33], v[32:33], v[32:33]
	v_pk_mul_f32 v[34:35], v[34:35], v[34:35]
	v_max_f32_e32 v40, 0, v48
	v_max_f32_e32 v42, 0, v49
	v_max_f32_e32 v41, 0, v50
	v_max_f32_e32 v43, 0, v51
	v_max_f32_e32 v44, 0, v53
	v_max_f32_e32 v46, 0, v54
	v_max_f32_e32 v45, 0, v55
	v_max_f32_e32 v47, 0, v56
	v_pk_mul_f32 v[36:37], v[36:37], v[36:37]
	v_pk_mul_f32 v[38:39], v[38:39], v[38:39]
	v_add_co_u32_e32 v50, vcc, s7, v112
	v_pk_mul_f32 v[40:41], v[40:41], v[40:41]
	v_pk_mul_f32 v[44:45], v[44:45], v[44:45]
	v_pk_mul_f32 v[42:43], v[42:43], v[42:43]
	v_pk_mul_f32 v[46:47], v[46:47], v[46:47]
	v_lshl_add_u64 v[48:49], v[112:113], 0, s[8:9]
	v_addc_co_u32_e32 v51, vcc, 0, v113, vcc
	s_mov_b32 s7, 0x280000
	s_mov_b64 s[8:9], 0x280000
	v_mul_f32_e32 v52, v247, v247
	v_pk_mul_f32 v[32:33], v[32:33], v[52:53] op_sel_hi:[1,0]
	v_pk_mul_f32 v[34:35], v[34:35], v[52:53] op_sel_hi:[1,0]
	v_pk_mul_f32 v[36:37], v[36:37], v[52:53] op_sel_hi:[1,0]
	v_pk_mul_f32 v[38:39], v[38:39], v[52:53] op_sel_hi:[1,0]
	v_cvt_pk_bf16_f32 v32, v32, v33
	v_cvt_pk_bf16_f32 v33, v36, v37
	v_cvt_pk_bf16_f32 v34, v34, v35
	v_pk_mul_f32 v[44:45], v[44:45], v[52:53] op_sel_hi:[1,0]
	v_cvt_pk_bf16_f32 v35, v38, v39
	v_pk_mul_f32 v[40:41], v[40:41], v[52:53] op_sel_hi:[1,0]
	v_pk_mul_f32 v[46:47], v[46:47], v[52:53] op_sel_hi:[1,0]
	v_pk_mul_f32 v[42:43], v[42:43], v[52:53] op_sel_hi:[1,0]
	global_store_dwordx4 v[50:51], v[32:35], off
	v_max_f32_e32 v38, v18, v18
	v_max_f32_e32 v18, 0, v24
	v_cvt_pk_bf16_f32 v32, v40, v41
	v_cvt_pk_bf16_f32 v33, v44, v45
	v_cvt_pk_bf16_f32 v34, v42, v43
	v_cvt_pk_bf16_f32 v35, v46, v47
	global_store_dwordx4 v[48:49], v[32:35], off offset:256
	s_nop 0
	v_max_f32_e32 v40, v19, v19
	v_max_f32_e32 v33, v16, v16
	v_max_f32_e32 v35, v17, v17
	v_max_f32_e32 v16, 0, v28
	v_max_f32_e32 v17, 0, v29
	v_max_f32_e32 v19, 0, v25
	v_max_f32_e32 v32, v20, v20
	v_max_f32_e32 v34, v21, v21
	v_max_f32_e32 v37, v22, v22
	v_max_f32_e32 v39, v23, v23
	v_max_f32_e32 v20, 0, v30
	v_max_f32_e32 v22, 0, v26
	v_max_f32_e32 v21, 0, v31
	v_max_f32_e32 v23, 0, v27
	v_pk_mul_f32 v[16:17], v[16:17], v[16:17]
	v_pk_mul_f32 v[18:19], v[18:19], v[18:19]
	v_max_f32_e32 v24, 0, v32
	v_max_f32_e32 v26, 0, v33
	v_max_f32_e32 v25, 0, v34
	v_max_f32_e32 v27, 0, v35
	v_max_f32_e32 v28, 0, v37
	v_max_f32_e32 v30, 0, v38
	v_max_f32_e32 v29, 0, v39
	v_max_f32_e32 v31, 0, v40
	v_pk_mul_f32 v[20:21], v[20:21], v[20:21]
	v_pk_mul_f32 v[22:23], v[22:23], v[22:23]
	v_add_co_u32_e32 v34, vcc, s7, v112
	v_pk_mul_f32 v[24:25], v[24:25], v[24:25]
	v_pk_mul_f32 v[28:29], v[28:29], v[28:29]
	v_pk_mul_f32 v[26:27], v[26:27], v[26:27]
	v_pk_mul_f32 v[30:31], v[30:31], v[30:31]
	v_lshl_add_u64 v[32:33], v[112:113], 0, s[8:9]
	v_addc_co_u32_e32 v35, vcc, 0, v113, vcc
	s_mov_b32 s7, 0x2c0000
	s_andn2_b64 vcc, exec, s[42:43]
	s_mov_b64 s[8:9], 0x2c0000
	v_mul_f32_e32 v36, v248, v248
	v_pk_mul_f32 v[16:17], v[16:17], v[36:37] op_sel_hi:[1,0]
	v_pk_mul_f32 v[18:19], v[18:19], v[36:37] op_sel_hi:[1,0]
	v_pk_mul_f32 v[20:21], v[20:21], v[36:37] op_sel_hi:[1,0]
	v_pk_mul_f32 v[22:23], v[22:23], v[36:37] op_sel_hi:[1,0]
	v_cvt_pk_bf16_f32 v16, v16, v17
	v_cvt_pk_bf16_f32 v17, v20, v21
	v_cvt_pk_bf16_f32 v18, v18, v19
	v_pk_mul_f32 v[28:29], v[28:29], v[36:37] op_sel_hi:[1,0]
	v_cvt_pk_bf16_f32 v19, v22, v23
	v_pk_mul_f32 v[24:25], v[24:25], v[36:37] op_sel_hi:[1,0]
	v_pk_mul_f32 v[30:31], v[30:31], v[36:37] op_sel_hi:[1,0]
	v_pk_mul_f32 v[26:27], v[26:27], v[36:37] op_sel_hi:[1,0]
	global_store_dwordx4 v[34:35], v[16:19], off
	v_max_f32_e32 v22, v2, v2
	v_max_f32_e32 v2, 0, v8
	v_cvt_pk_bf16_f32 v16, v24, v25
	v_cvt_pk_bf16_f32 v17, v28, v29
	v_cvt_pk_bf16_f32 v18, v26, v27
	v_cvt_pk_bf16_f32 v19, v30, v31
	global_store_dwordx4 v[32:33], v[16:19], off offset:256
	s_nop 0
	v_max_f32_e32 v24, v3, v3
	v_max_f32_e32 v17, v0, v0
	v_max_f32_e32 v19, v1, v1
	v_max_f32_e32 v0, 0, v12
	v_max_f32_e32 v1, 0, v13
	v_max_f32_e32 v3, 0, v9
	v_max_f32_e32 v16, v4, v4
	v_max_f32_e32 v18, v5, v5
	v_max_f32_e32 v21, v6, v6
	v_max_f32_e32 v23, v7, v7
	v_max_f32_e32 v4, 0, v14
	v_max_f32_e32 v6, 0, v10
	v_max_f32_e32 v5, 0, v15
	v_max_f32_e32 v7, 0, v11
	v_pk_mul_f32 v[0:1], v[0:1], v[0:1]
	v_pk_mul_f32 v[2:3], v[2:3], v[2:3]
	v_max_f32_e32 v8, 0, v16
	v_max_f32_e32 v10, 0, v17
	v_max_f32_e32 v9, 0, v18
	v_max_f32_e32 v11, 0, v19
	v_max_f32_e32 v12, 0, v21
	v_max_f32_e32 v14, 0, v22
	v_max_f32_e32 v13, 0, v23
	v_max_f32_e32 v15, 0, v24
	v_pk_mul_f32 v[4:5], v[4:5], v[4:5]
	v_pk_mul_f32 v[6:7], v[6:7], v[6:7]
	v_add_co_u32_e64 v18, s[42:43], s7, v112
	v_pk_mul_f32 v[8:9], v[8:9], v[8:9]
	v_pk_mul_f32 v[12:13], v[12:13], v[12:13]
	v_pk_mul_f32 v[10:11], v[10:11], v[10:11]
	v_pk_mul_f32 v[14:15], v[14:15], v[14:15]
	v_lshl_add_u64 v[16:17], v[112:113], 0, s[8:9]
	v_addc_co_u32_e64 v19, s[42:43], 0, v113, s[42:43]
	s_mov_b64 s[8:9], -1
	v_mul_f32_e32 v20, v249, v249
	v_pk_mul_f32 v[0:1], v[0:1], v[20:21] op_sel_hi:[1,0]
	v_pk_mul_f32 v[2:3], v[2:3], v[20:21] op_sel_hi:[1,0]
	v_pk_mul_f32 v[4:5], v[4:5], v[20:21] op_sel_hi:[1,0]
	v_pk_mul_f32 v[6:7], v[6:7], v[20:21] op_sel_hi:[1,0]
	v_cvt_pk_bf16_f32 v0, v0, v1
	v_cvt_pk_bf16_f32 v1, v4, v5
	v_cvt_pk_bf16_f32 v2, v2, v3
	v_pk_mul_f32 v[12:13], v[12:13], v[20:21] op_sel_hi:[1,0]
	v_cvt_pk_bf16_f32 v3, v6, v7
	v_pk_mul_f32 v[8:9], v[8:9], v[20:21] op_sel_hi:[1,0]
	v_pk_mul_f32 v[14:15], v[14:15], v[20:21] op_sel_hi:[1,0]
	v_pk_mul_f32 v[10:11], v[10:11], v[20:21] op_sel_hi:[1,0]
	global_store_dwordx4 v[18:19], v[0:3], off
	s_nop 1
	v_cvt_pk_bf16_f32 v0, v8, v9
	v_cvt_pk_bf16_f32 v1, v12, v13
	v_cvt_pk_bf16_f32 v2, v10, v11
	v_cvt_pk_bf16_f32 v3, v14, v15
	global_store_dwordx4 v[16:17], v[0:3], off offset:256
	s_cbranch_vccnz .LBB0_597
	s_andn2_b64 vcc, exec, s[76:77]
	s_cbranch_vccnz .LBB0_596
	s_barrier
	s_branch .LBB0_596
